# attention step: waves 4-7 staggered by 2048 cycles behind their SIMD partners (MFMA beside softmax VALU)
# speedup vs baseline: 1.0041x; 1.0012x over previous
; #define LAS __attribute__((address_space(3)))
; __device__ __forceinline__ void attn_unit_lds(const f16* __restrict__ Q, f16* __restrict__ ATT, const LAS unsigned char* lds, const LAS float* bias, int b, int r, int h, int qb, int lane) {
;     const int i = lane & 15, g = lane >> 4;
;     const int c0q = qb * 16, c0k = min(max(c0q - 8, 0), 32), rs = attn_rs(r);
;     const int qc = c0q + i, cs = min(max(qc - 8, 0), GW - 16);
;     const f16* qp = Q + (size_t)(b * SEQ + r * GW + qc) * DA + h * HD + 8 * g;
;     const f16x8 qf0 = *(const f16x8*)qp, qf1 = *(const f16x8*)(qp + 32);
;     f32x4 st[8][2];
; #pragma unroll
;     for (int kr = 0; kr < 8; ++kr) {
;         const int slot = ((rs + kr) % 9) * 16384;
; #pragma unroll
;         for (int ct = 0; ct < 2; ++ct) {
;             const int key = c0k + 16 * ct + i, sw = (key >> 1) & 7; const LAS unsigned char* kp = lds + slot + key * 128;
;             const f16x8 k0 = *(const LAS f16x8*)(kp + ((g ^ sw) * 16)), k1 = *(const LAS f16x8*)(kp + (((g + 4) ^ sw) * 16));
;             f32x4 a = (f32x4){0.f, 0.f, 0.f, 0.f};
;             a = __builtin_amdgcn_mfma_f32_16x16x32_f16(k0, qf0, a, 0, 0, 0);
;             a = __builtin_amdgcn_mfma_f32_16x16x32_f16(k1, qf1, a, 0, 0, 0);
;             st[kr][ct] = a;
;         }
;     }
.LBB0_652:
	v_ashrrev_i32_e32 v73, 31, v72
	v_lshlrev_b64 v[78:79], 10, v[72:73]
	v_lshl_add_u64 v[16:17], v[74:75], 0, v[78:79]
	global_load_dwordx4 v[54:57], v[16:17], off
	global_load_dwordx4 v[38:41], v[16:17], off offset:64
	v_readlane_b32 s27, v254, 6
	s_cmp_lt_u32 s27, 4
	s_cbranch_scc1 .Lstag_skip
	s_sleep 32
.Lstag_skip:
	s_add_i32 s27, s15, s17
	s_max_i32 s27, s27, 4
	s_add_i32 s27, s27, -4
	s_min_u32 s27, s27, 24
	s_mul_i32 s28, s27, 29
	s_mul_i32 s36, s27, 57
	s_lshr_b32 s28, s28, 8
	s_add_i32 s29, s36, 57
	s_mul_i32 s28, s28, 9
	s_lshr_b32 s29, s29, 9
	s_sub_i32 s28, s27, s28
	s_mul_i32 s29, s29, 9
	s_and_b32 s28, s28, 0xff
	s_sub_i32 s29, s27, s29
	s_lshl_b32 s28, s28, 14
	s_add_i32 s29, s29, 1
	s_add_i32 s37, s28, 0
	s_and_b32 s28, s29, 0xff
	s_lshl_b32 s28, s28, 14
	s_add_i32 s35, s28, 0
	v_add_u32_e32 v73, s37, v82
	v_add_u32_e32 v110, s35, v82
	v_add_u32_e32 v20, v73, v83
	v_add_u32_e32 v28, v110, v83
	ds_read_b128 v[16:19], v20
	ds_read_b128 v[24:27], v28
	ds_read_b128 v[20:23], v20 offset:2048
	ds_read_b128 v[28:31], v28 offset:2048
	v_add_u32_e32 v73, v73, v84
	ds_read_b128 v[106:109], v73
	ds_read_b128 v[114:117], v73 offset:2048
	s_add_i32 s30, s36, 0x72
	s_lshr_b32 s30, s30, 9
	s_add_i32 s31, s36, 0xab
	s_mul_i32 s30, s30, 9
	s_lshr_b32 s31, s31, 9
	s_sub_i32 s30, s27, s30
	s_mul_i32 s31, s31, 9
	s_add_i32 s30, s30, 2
	s_sub_i32 s31, s27, s31
	s_and_b32 s29, s30, 0xff
	s_add_i32 s31, s31, 3
	s_lshl_b32 s28, s29, 14
	v_add_u32_e32 v73, v110, v84
	s_add_i32 s34, s28, 0
	s_and_b32 s28, s31, 0xff
	s_lshl_b32 s28, s28, 14
	s_add_i32 s31, s28, 0
	v_add_u32_e32 v111, s34, v82
	v_add_u32_e32 v112, s31, v82
	v_add_u32_e32 v42, v111, v83
	v_add_u32_e32 v50, v112, v83
	ds_read_b128 v[34:37], v42
	ds_read_b128 v[46:49], v50
	ds_read_b128 v[42:45], v42 offset:2048
	ds_read_b128 v[50:53], v50 offset:2048
	s_add_i32 s28, s36, 0xe4
	s_lshr_b32 s28, s28, 9
	s_mul_i32 s28, s28, 9
	s_sub_i32 s28, s27, s28
	s_add_i32 s28, s28, 4
	s_and_b32 s28, s28, 0xff
	s_lshl_b32 s28, s28, 14
	s_add_i32 s30, s28, 0
	s_add_i32 s28, s36, 0x11d
	s_lshr_b32 s28, s28, 9
	s_mul_i32 s28, s28, 9
	s_sub_i32 s28, s27, s28
	s_add_i32 s28, s28, 5
	s_and_b32 s28, s28, 0xff
	s_lshl_b32 s28, s28, 14
	s_add_i32 s29, s28, 0
	s_add_i32 s28, s36, 0x156
	s_lshr_b32 s28, s28, 9
	s_mul_i32 s28, s28, 9
	s_sub_i32 s28, s27, s28
	s_add_i32 s28, s28, 6
	s_and_b32 s28, s28, 0xff
	s_waitcnt vmcnt(1) lgkmcnt(9)
	v_mfma_f32_16x16x32_f16 v[16:19], v[16:19], v[54:57], 0
	s_lshl_b32 s28, s28, 14
	s_add_i32 s28, s28, 0
	s_addk_i32 s36, 0x18f
	s_waitcnt lgkmcnt(7)
	v_mfma_f32_16x16x32_f16 v[20:23], v[20:23], v[54:57], 0
	s_lshr_b32 s36, s36, 9
	s_mul_i32 s36, s36, 9
	s_sub_i32 s27, s27, s36
	s_waitcnt vmcnt(0) lgkmcnt(5)
	v_mfma_f32_16x16x32_f16 v[106:109], v[106:109], v[38:41], v[16:19]
	s_add_i32 s27, s27, 7
	s_and_b32 s27, s27, 0xff
	s_lshl_b32 s27, s27, 14
	ds_read_b128 v[16:19], v73
	s_waitcnt lgkmcnt(5)
	v_mfma_f32_16x16x32_f16 v[114:117], v[114:117], v[38:41], v[20:23]
	s_add_i32 s27, s27, 0
	s_max_i32 s36, s24, 4
	s_add_i32 s36, s36, -4
	ds_read_b128 v[20:23], v73 offset:2048
	v_mfma_f32_16x16x32_f16 v[24:27], v[24:27], v[54:57], 0
	v_add_u32_e32 v73, v111, v84
	s_min_u32 s36, s36, 24
	s_add_i32 s36, s36, s16
	v_mfma_f32_16x16x32_f16 v[28:31], v[28:31], v[54:57], 0
	s_mulk_i32 s36, 0x7c
	s_add_i32 s36, s36, 0
	s_add_i32 s36, s36, 0x24000
	s_waitcnt lgkmcnt(1)
	v_mfma_f32_16x16x32_f16 v[118:121], v[16:19], v[38:41], v[24:27]
	ds_read_b128 v[16:19], v73
	v_cvt_pk_f16_f32 v106, v106, v107
	s_mov_b32 s42, 0xfb53
	s_waitcnt lgkmcnt(1)
	v_mfma_f32_16x16x32_f16 v[122:125], v[20:23], v[38:41], v[28:31]
	ds_read_b128 v[20:23], v73 offset:2048
	v_add_u32_e32 v24, v112, v84
	v_lshl_add_u32 v112, v86, 2, s36
	v_mfma_f32_16x16x32_f16 v[34:37], v[34:37], v[54:57], 0
	v_mfma_f32_16x16x32_f16 v[42:45], v[42:45], v[54:57], 0
	s_waitcnt lgkmcnt(1)
	v_mfma_f32_16x16x32_f16 v[126:129], v[16:19], v[38:41], v[34:37]
	ds_read_b128 v[16:19], v24
	s_waitcnt lgkmcnt(1)
	v_mfma_f32_16x16x32_f16 v[130:133], v[20:23], v[38:41], v[42:45]
	ds_read_b128 v[20:23], v24 offset:2048
	v_mfma_f32_16x16x32_f16 v[50:53], v[50:53], v[54:57], 0
	v_mfma_f32_16x16x32_f16 v[46:49], v[46:49], v[54:57], 0
	s_waitcnt lgkmcnt(0)
	v_mfma_f32_16x16x32_f16 v[50:53], v[20:23], v[38:41], v[50:53]
	v_add_u32_e32 v20, s30, v82
	v_add_u32_e32 v21, v20, v83
	v_add_u32_e32 v28, v20, v84
	v_mfma_f32_16x16x32_f16 v[134:137], v[16:19], v[38:41], v[46:49]
	ds_read_b128 v[16:19], v21
	ds_read_b128 v[20:23], v21 offset:2048
	ds_read_b128 v[24:27], v28
	ds_read_b128 v[28:31], v28 offset:2048
	s_waitcnt lgkmcnt(3)
	v_mfma_f32_16x16x32_f16 v[16:19], v[16:19], v[54:57], 0
	v_cvt_pk_f16_f32 v50, v50, v51
	v_cvt_pk_f16_f32 v52, v52, v53
	s_waitcnt lgkmcnt(1)
	v_mfma_f32_16x16x32_f16 v[42:45], v[24:27], v[38:41], v[16:19]
	v_add_u32_e32 v24, s29, v82
	v_add_u32_e32 v25, v24, v83
	v_add_u32_e32 v34, v24, v84
	v_mfma_f32_16x16x32_f16 v[16:19], v[20:23], v[54:57], 0
	s_waitcnt lgkmcnt(0)
	v_mfma_f32_16x16x32_f16 v[20:23], v[28:31], v[38:41], v[16:19]
	s_nop 1
	v_cvt_pk_f16_f32 v42, v42, v43
	v_cvt_pk_f16_f32 v44, v44, v45
	s_nop 1
	ds_read_b128 v[16:19], v25
	ds_read_b128 v[24:27], v25 offset:2048
	s_waitcnt lgkmcnt(1)
	v_mfma_f32_16x16x32_f16 v[16:19], v[16:19], v[54:57], 0
	ds_read_b128 v[28:31], v34
	ds_read_b128 v[34:37], v34 offset:2048
	v_cvt_pk_f16_f32 v20, v20, v21
	v_cvt_pk_f16_f32 v22, v22, v23
	s_waitcnt lgkmcnt(1)
	v_mfma_f32_16x16x32_f16 v[46:49], v[28:31], v[38:41], v[16:19]
	v_add_u32_e32 v28, s28, v82
	v_add_u32_e32 v29, v28, v83
	v_add_u32_e32 v73, v28, v84
	v_mfma_f32_16x16x32_f16 v[16:19], v[24:27], v[54:57], 0
	s_waitcnt lgkmcnt(0)
; #define LAS __attribute__((address_space(3)))
; __device__ __forceinline__ void attn_unit_lds(const f16* __restrict__ Q, f16* __restrict__ ATT, const LAS unsigned char* lds, const LAS float* bias, int b, int r, int h, int qb, int lane) {
;     ...
;     f16x2 sp[8][2][2], mk[2][2]; int co[2][4];
; #pragma unroll
;     for (int ct = 0; ct < 2; ++ct)
; #pragma unroll
;         for (int e = 0; e < 4; ++e) { const int kc = c0k + 16 * ct + 4 * g + e; const bool valid = (kc >= cs) && (kc < cs + 16);
;             co[ct][e] = min(max(kc - qc + 15, 0), 30); mk[ct][e >> 1][e & 1] = valid ? (f16)0.f : (f16)(-60000.f); }
;     f16x2 mxv = {(f16)(-60000.f), (f16)(-60000.f)};
; #pragma unroll
;     for (int kr = 0; kr < 8; ++kr) {
;         const LAS float* brow = bias + (rs + kr - r + 7) * 31;
; #pragma unroll
;         for (int ct = 0; ct < 2; ++ct)
; #pragma unroll
;             for (int q = 0; q < 2; ++q) {
;                 const f16x2 b2 = {(f16)brow[co[ct][2 * q]], (f16)brow[co[ct][2 * q + 1]]};
;                 const f16x2 s2 = (f16x2){(f16)st[kr][ct][2 * q], (f16)st[kr][ct][2 * q + 1]} * (f16)0.125f + b2 + mk[ct][q];
;                 sp[kr][ct][q] = s2; mxv = __builtin_elementwise_max(mxv, s2);
;             }
;     }
	v_mfma_f32_16x16x32_f16 v[24:27], v[34:37], v[38:41], v[16:19]
	ds_read_b128 v[34:37], v29 offset:2048
	s_nop 4
	ds_read_b128 v[16:19], v29
	s_waitcnt lgkmcnt(0)
	v_mfma_f32_16x16x32_f16 v[16:19], v[16:19], v[54:57], 0
	ds_read_b128 v[28:31], v73
	ds_read_b128 v[138:141], v73 offset:2048
	v_add_u32_e32 v73, s27, v82
	v_add_u32_e32 v110, v73, v83
	s_waitcnt lgkmcnt(1)
	v_mfma_f32_16x16x32_f16 v[28:31], v[28:31], v[38:41], v[16:19]
	v_add_u32_e32 v73, v73, v84
	ds_read_b128 v[142:145], v73
	ds_read_b128 v[146:149], v73 offset:2048
	v_mfma_f32_16x16x32_f16 v[16:19], v[34:37], v[54:57], 0
	ds_read_b128 v[34:37], v110
	v_lshl_add_u32 v73, v85, 2, s36
	v_cvt_pk_f16_f32 v26, v26, v27
	s_waitcnt lgkmcnt(3)
	v_mfma_f32_16x16x32_f16 v[16:19], v[138:141], v[38:41], v[16:19]
	ds_read_b128 v[138:141], v110 offset:2048
	ds_read2_b32 v[110:111], v73 offset0:217 offset1:248
	v_add_u32_e32 v73, 0x400, v73
	s_waitcnt lgkmcnt(2)
	v_mfma_f32_16x16x32_f16 v[34:37], v[34:37], v[54:57], 0
	s_nop 2
	v_cvt_pk_f16_f32 v16, v16, v17
	s_waitcnt lgkmcnt(1)
	v_mfma_f32_16x16x32_f16 v[54:57], v[138:141], v[54:57], 0
	ds_read2_b32 v[138:139], v112 offset0:217 offset1:248
	v_add_u32_e32 v112, 0x400, v112
	v_cvt_pk_f16_f32 v18, v18, v19
	v_mfma_f32_16x16x32_f16 v[34:37], v[142:145], v[38:41], v[34:37]
	v_lshl_add_u32 v144, v89, 2, s36
	s_waitcnt lgkmcnt(0)
	v_cvt_pk_f16_f32 v110, v110, v138
	v_lshl_add_u32 v138, v88, 2, s36
	v_mfma_f32_16x16x32_f16 v[38:41], v[146:149], v[38:41], v[54:57]
	v_pk_fma_f16 v106, v106, s46, v110 op_sel_hi:[1,0,1]
	v_lshl_add_u32 v146, v91, 2, s36
	v_lshl_add_u32 v147, v92, 2, s36
	ds_read2_b32 v[54:55], v138 offset0:217 offset1:248
	ds_read2_b32 v[56:57], v144 offset0:217 offset1:248
	v_pk_add_f16 v145, v87, v106
	ds_read2_b32 v[106:107], v146 offset0:217 offset1:248
	ds_read2_b32 v[140:141], v147 offset0:217 offset1:248
	v_lshl_add_u32 v149, v95, 2, s36
	s_waitcnt lgkmcnt(2)
	v_cvt_pk_f16_f32 v54, v54, v56
	v_cvt_pk_f16_f32 v56, v108, v109
	v_pk_fma_f16 v54, v56, s46, v54 op_sel_hi:[1,0,1]
	s_waitcnt lgkmcnt(0)
	v_cvt_pk_f16_f32 v56, v106, v140
	v_lshl_add_u32 v140, v94, 2, s36
	ds_read2_b32 v[108:109], v140 offset0:217 offset1:248
	ds_read2_b32 v[142:143], v149 offset0:217 offset1:248
	v_cvt_pk_f16_f32 v106, v114, v115
	v_pk_fma_f16 v56, v106, s46, v56 op_sel_hi:[1,0,1]
	v_cvt_pk_f16_f32 v106, v116, v117
	v_pk_add_f16 v150, v93, v56
	s_waitcnt lgkmcnt(0)
	v_cvt_pk_f16_f32 v56, v108, v142
	v_pk_fma_f16 v56, v106, s46, v56 op_sel_hi:[1,0,1]
	v_cvt_pk_f16_f32 v106, v118, v119
	v_pk_add_f16 v142, v96, v56
	v_cvt_pk_f16_f32 v56, v111, v139
	v_pk_max_f16 v110, v145, s42 op_sel_hi:[1,0]
	v_pk_add_f16 v148, v90, v54
	v_pk_fma_f16 v56, v106, s46, v56 op_sel_hi:[1,0,1]
	v_pk_max_f16 v54, v110, v148
	v_pk_add_f16 v139, v87, v56
	v_cvt_pk_f16_f32 v55, v55, v57
	v_cvt_pk_f16_f32 v56, v120, v121
	v_pk_max_f16 v54, v54, v150
	v_pk_fma_f16 v55, v56, s46, v55 op_sel_hi:[1,0,1]
	v_pk_max_f16 v54, v54, v142
	v_pk_add_f16 v120, v90, v55
	v_cvt_pk_f16_f32 v55, v107, v141
	v_cvt_pk_f16_f32 v56, v122, v123
	v_pk_max_f16 v54, v54, v139
	v_pk_fma_f16 v55, v56, s46, v55 op_sel_hi:[1,0,1]
	v_pk_max_f16 v54, v54, v120
	v_pk_add_f16 v121, v93, v55
	ds_read2_b32 v[56:57], v112 offset0:23 offset1:54
	v_pk_max_f16 v106, v54, v121
	ds_read2_b32 v[54:55], v73 offset0:23 offset1:54
	v_cvt_pk_f16_f32 v107, v109, v143
	v_cvt_pk_f16_f32 v108, v124, v125
	v_pk_fma_f16 v107, v108, s46, v107 op_sel_hi:[1,0,1]
	v_add_u32_e32 v123, 0x400, v138
	v_pk_add_f16 v122, v96, v107
	s_waitcnt lgkmcnt(0)
	v_cvt_pk_f16_f32 v54, v54, v56
	v_add_u32_e32 v124, 0x400, v144
	v_cvt_pk_f16_f32 v56, v126, v127
	v_pk_max_f16 v110, v106, v122
	ds_read2_b32 v[106:107], v123 offset0:23 offset1:54
	ds_read2_b32 v[108:109], v124 offset0:23 offset1:54
	v_pk_fma_f16 v54, v56, s46, v54 op_sel_hi:[1,0,1]
	v_add_u32_e32 v126, 0x400, v146
	v_pk_add_f16 v125, v87, v54
	v_add_u32_e32 v127, 0x400, v147
	v_pk_max_f16 v54, v110, v125
	ds_read2_b32 v[110:111], v126 offset0:23 offset1:54
	ds_read2_b32 v[114:115], v127 offset0:23 offset1:54
	s_waitcnt lgkmcnt(2)
	v_cvt_pk_f16_f32 v56, v106, v108
	v_cvt_pk_f16_f32 v106, v128, v129
	v_pk_fma_f16 v56, v106, s46, v56 op_sel_hi:[1,0,1]
	v_cvt_pk_f16_f32 v106, v130, v131
	v_pk_add_f16 v128, v90, v56
	s_waitcnt lgkmcnt(0)
	v_cvt_pk_f16_f32 v56, v110, v114
	v_add_u32_e32 v110, 0x400, v140
	v_add_u32_e32 v114, 0x400, v149
	ds_read2_b32 v[116:117], v110 offset0:23 offset1:54
	ds_read2_b32 v[118:119], v114 offset0:23 offset1:54
	v_pk_fma_f16 v56, v106, s46, v56 op_sel_hi:[1,0,1]
	v_cvt_pk_f16_f32 v106, v132, v133
	v_pk_add_f16 v129, v93, v56
	v_cvt_pk_f16_f32 v55, v55, v57
	s_waitcnt lgkmcnt(0)
	v_cvt_pk_f16_f32 v56, v116, v118
	v_pk_fma_f16 v56, v106, s46, v56 op_sel_hi:[1,0,1]
	v_pk_max_f16 v54, v54, v128
	v_pk_add_f16 v116, v96, v56
	v_cvt_pk_f16_f32 v56, v134, v135
	v_pk_fma_f16 v55, v56, s46, v55 op_sel_hi:[1,0,1]
	v_cvt_pk_f16_f32 v56, v136, v137
	v_pk_add_f16 v118, v87, v55
	v_cvt_pk_f16_f32 v55, v107, v109
	v_pk_max_f16 v54, v54, v129
	v_pk_fma_f16 v55, v56, s46, v55 op_sel_hi:[1,0,1]
	v_pk_max_f16 v54, v54, v116
	v_pk_add_f16 v130, v90, v55
	v_cvt_pk_f16_f32 v55, v111, v115
	v_pk_max_f16 v54, v54, v118
	v_pk_fma_f16 v50, v50, s46, v55 op_sel_hi:[1,0,1]
	v_pk_max_f16 v54, v54, v130
	v_pk_add_f16 v111, v93, v50
	v_cvt_pk_f16_f32 v57, v117, v119
	v_pk_max_f16 v56, v54, v111
	ds_read2_b32 v[50:51], v73 offset0:85 offset1:116
	ds_read2_b32 v[54:55], v112 offset0:85 offset1:116
	v_pk_fma_f16 v52, v52, s46, v57 op_sel_hi:[1,0,1]
	s_mov_b32 s36, 0x3fb8aa3b
	v_pk_add_f16 v115, v96, v52
	s_waitcnt lgkmcnt(0)
; #define LAS __attribute__((address_space(3)))
; __device__ __forceinline__ float shx(float v, int mask) { return __builtin_bit_cast(float, __builtin_amdgcn_ds_bpermute((lane_now() ^ mask) << 2, __builtin_bit_cast(int, v))); }
; __device__ __forceinline__ void attn_unit_lds(const f16* __restrict__ Q, f16* __restrict__ ATT, const LAS unsigned char* lds, const LAS float* bias, int b, int r, int h, int qb, int lane) {
;     ...
;     f16x2 mxv = {(f16)(-60000.f), (f16)(-60000.f)};
; #pragma unroll
;     for (int kr = 0; kr < 8; ++kr) {
;         const LAS float* brow = bias + (rs + kr - r + 7) * 31;
; #pragma unroll
;         for (int ct = 0; ct < 2; ++ct)
; #pragma unroll
;             for (int q = 0; q < 2; ++q) {
;                 const f16x2 b2 = {(f16)brow[co[ct][2 * q]], (f16)brow[co[ct][2 * q + 1]]};
;                 const f16x2 s2 = (f16x2){(f16)st[kr][ct][2 * q], (f16)st[kr][ct][2 * q + 1]} * (f16)0.125f + b2 + mk[ct][q];
;                 sp[kr][ct][q] = s2; mxv = __builtin_elementwise_max(mxv, s2);
;             }
;     }
;     float mx = fmaxf((float)mxv[0], (float)mxv[1]);
;     mx = fmaxf(mx, shx(mx, 16)); mx = fmaxf(mx, shx(mx, 32));
;     const f16 mxl = (f16)(mx * 1.44269504f); const f16x2 ml = {mxl, mxl};
;     f16x2 sumv = {(f16)0.f, (f16)0.f};
; #pragma unroll
;     for (int kr = 0; kr < 8; ++kr)
; #pragma unroll
;         for (int ct = 0; ct < 2; ++ct)
; #pragma unroll
;             for (int q = 0; q < 2; ++q) { const f16x2 a = sp[kr][ct][q] * (f16)1.44269504f - ml; f16x2 pe; pe[0] = __builtin_exp2f16(a[0]); pe[1] = __builtin_exp2f16(a[1]); sp[kr][ct][q] = pe; sumv += pe; }
;     float sum = (float)sumv[0] + (float)sumv[1];
;     sum += shx(sum, 16); sum += shx(sum, 32);
	v_cvt_pk_f16_f32 v50, v50, v54
	v_pk_max_f16 v106, v56, v115
	ds_read2_b32 v[52:53], v123 offset0:85 offset1:116
	ds_read2_b32 v[56:57], v124 offset0:85 offset1:116
	v_pk_fma_f16 v42, v42, s46, v50 op_sel_hi:[1,0,1]
	s_waitcnt lgkmcnt(0)
	v_cvt_pk_f16_f32 v52, v52, v56
	v_pk_add_f16 v50, v87, v42
	v_pk_fma_f16 v44, v44, s46, v52 op_sel_hi:[1,0,1]
	v_pk_max_f16 v54, v106, v50
	ds_read2_b32 v[42:43], v126 offset0:85 offset1:116
	ds_read2_b32 v[106:107], v127 offset0:85 offset1:116
	v_pk_add_f16 v52, v90, v44
	ds_read2_b32 v[44:45], v110 offset0:85 offset1:116
	ds_read2_b32 v[108:109], v114 offset0:85 offset1:116
	v_pk_max_f16 v54, v54, v52
	s_waitcnt lgkmcnt(2)
	v_cvt_pk_f16_f32 v42, v42, v106
	v_pk_fma_f16 v20, v20, s46, v42 op_sel_hi:[1,0,1]
	s_waitcnt lgkmcnt(0)
	v_cvt_pk_f16_f32 v21, v44, v108
	v_pk_add_f16 v56, v93, v20
	v_pk_fma_f16 v21, v22, s46, v21 op_sel_hi:[1,0,1]
	v_pk_max_f16 v20, v54, v56
	v_pk_add_f16 v54, v96, v21
	v_cvt_pk_f16_f32 v21, v51, v55
	v_cvt_pk_f16_f32 v22, v46, v47
	v_pk_fma_f16 v21, v22, s46, v21 op_sel_hi:[1,0,1]
	v_cvt_pk_f16_f32 v22, v48, v49
	v_pk_add_f16 v46, v87, v21
	v_cvt_pk_f16_f32 v21, v53, v57
	v_pk_fma_f16 v21, v22, s46, v21 op_sel_hi:[1,0,1]
	v_pk_max_f16 v20, v20, v54
	v_pk_add_f16 v47, v90, v21
	v_cvt_pk_f16_f32 v21, v43, v107
	v_cvt_pk_f16_f32 v22, v24, v25
	v_pk_max_f16 v20, v20, v46
	v_pk_fma_f16 v21, v22, s46, v21 op_sel_hi:[1,0,1]
	v_pk_max_f16 v20, v20, v47
	v_pk_add_f16 v48, v93, v21
	v_cvt_pk_f16_f32 v25, v45, v109
	v_pk_max_f16 v24, v20, v48
	ds_read2_b32 v[20:21], v73 offset0:147 offset1:178
	ds_read2_b32 v[22:23], v112 offset0:147 offset1:178
	v_pk_fma_f16 v25, v26, s46, v25 op_sel_hi:[1,0,1]
	s_waitcnt lgkmcnt(0)
	v_cvt_pk_f16_f32 v20, v20, v22
	v_pk_add_f16 v49, v96, v25
	v_cvt_pk_f16_f32 v22, v28, v29
	v_pk_max_f16 v42, v24, v49
	ds_read2_b32 v[24:25], v123 offset0:147 offset1:178
	ds_read2_b32 v[26:27], v124 offset0:147 offset1:178
	v_pk_fma_f16 v20, v22, s46, v20 op_sel_hi:[1,0,1]
	s_waitcnt lgkmcnt(0)
	v_cvt_pk_f16_f32 v22, v24, v26
	v_pk_add_f16 v51, v87, v20
	v_cvt_pk_f16_f32 v24, v30, v31
	v_pk_max_f16 v20, v42, v51
	ds_read2_b32 v[28:29], v126 offset0:147 offset1:178
	ds_read2_b32 v[42:43], v127 offset0:147 offset1:178
	ds_read2_b32 v[30:31], v110 offset0:147 offset1:178
	ds_read2_b32 v[44:45], v114 offset0:147 offset1:178
	v_pk_fma_f16 v22, v24, s46, v22 op_sel_hi:[1,0,1]
	s_waitcnt lgkmcnt(0)
	v_cvt_pk_f16_f32 v17, v30, v44
	v_pk_fma_f16 v17, v18, s46, v17 op_sel_hi:[1,0,1]
	v_cvt_pk_f16_f32 v18, v34, v35
	v_pk_add_f16 v19, v96, v17
	v_cvt_pk_f16_f32 v17, v21, v23
	v_pk_add_f16 v53, v90, v22
	v_cvt_pk_f16_f32 v22, v28, v42
	v_pk_fma_f16 v17, v18, s46, v17 op_sel_hi:[1,0,1]
	v_pk_fma_f16 v16, v16, s46, v22 op_sel_hi:[1,0,1]
	v_pk_add_f16 v110, v87, v17
	v_cvt_pk_f16_f32 v17, v25, v27
	v_cvt_pk_f16_f32 v18, v36, v37
	v_pk_max_f16 v20, v20, v53
	v_pk_add_f16 v73, v93, v16
	v_pk_fma_f16 v17, v18, s46, v17 op_sel_hi:[1,0,1]
	v_pk_max_f16 v16, v20, v73
	v_pk_add_f16 v112, v90, v17
	v_cvt_pk_f16_f32 v17, v29, v43
	v_cvt_pk_f16_f32 v18, v38, v39
	v_pk_max_f16 v16, v16, v19
	v_pk_fma_f16 v17, v18, s46, v17 op_sel_hi:[1,0,1]
	v_pk_max_f16 v16, v16, v110
	v_pk_add_f16 v126, v93, v17
	v_cvt_pk_f16_f32 v17, v31, v45
	v_cvt_pk_f16_f32 v18, v40, v41
	v_pk_max_f16 v16, v16, v112
	v_pk_fma_f16 v17, v18, s46, v17 op_sel_hi:[1,0,1]
	v_pk_max_f16 v16, v16, v126
	v_pk_add_f16 v127, v96, v17
	v_mbcnt_lo_u32_b32 v17, -1, 0
	v_mbcnt_hi_u32_b32 v17, -1, v17
	s_nop 0
	v_pk_max_f16 v16, v16, v127
	v_lshlrev_b32_e32 v17, 2, v17
	v_max_f16_sdwa v16, v16, v16 dst_sel:DWORD dst_unused:UNUSED_PAD src0_sel:DWORD src1_sel:WORD_1
	v_cvt_f32_f16_e32 v16, v16
	v_xor_b32_e32 v17, 64, v17
	ds_bpermute_b32 v17, v17, v16
	s_waitcnt lgkmcnt(0)
	v_max_f32_e32 v17, v17, v17
	v_max_f32_e32 v16, v16, v17
	v_mbcnt_lo_u32_b32 v17, -1, 0
	v_mbcnt_hi_u32_b32 v17, -1, v17
	s_nop 0
	v_lshlrev_b32_e32 v17, 2, v17
	v_xor_b32_e32 v17, 0x80, v17
	ds_bpermute_b32 v17, v17, v16
	s_waitcnt lgkmcnt(0)
	v_max_f32_e32 v17, v17, v17
	v_max_f32_e32 v16, v16, v17
	v_fma_mixlo_f16 v131, v16, s36, 0
	v_pk_fma_f16 v16, v145, s51, v131 op_sel_hi:[1,0,0] neg_lo:[0,0,1] neg_hi:[0,0,1]
	v_pk_fma_f16 v18, v148, s51, v131 op_sel_hi:[1,0,0] neg_lo:[0,0,1] neg_hi:[0,0,1]
	v_exp_f16_e32 v17, v16
	v_exp_f16_sdwa v16, v16 dst_sel:DWORD dst_unused:UNUSED_PAD src0_sel:WORD_1
	v_exp_f16_e32 v20, v18
	v_exp_f16_sdwa v18, v18 dst_sel:DWORD dst_unused:UNUSED_PAD src0_sel:WORD_1
	v_pk_fma_f16 v21, v150, s51, v131 op_sel_hi:[1,0,0] neg_lo:[0,0,1] neg_hi:[0,0,1]
	v_pack_b32_f16 v42, v17, v16
	v_exp_f16_e32 v22, v21
	v_exp_f16_sdwa v21, v21 dst_sel:DWORD dst_unused:UNUSED_PAD src0_sel:WORD_1
	v_pk_fma_f16 v17, v142, s51, v131 op_sel_hi:[1,0,0] neg_lo:[0,0,1] neg_hi:[0,0,1]
	v_pack_b32_f16 v43, v20, v18
	v_exp_f16_e32 v18, v17
	v_exp_f16_sdwa v17, v17 dst_sel:DWORD dst_unused:UNUSED_PAD src0_sel:WORD_1
	v_pk_fma_f16 v20, v139, s51, v131 op_sel_hi:[1,0,0] neg_lo:[0,0,1] neg_hi:[0,0,1]
	v_pack_b32_f16 v44, v22, v21
	v_exp_f16_e32 v21, v20
	v_exp_f16_sdwa v20, v20 dst_sel:DWORD dst_unused:UNUSED_PAD src0_sel:WORD_1
	v_pack_b32_f16 v45, v18, v17
	v_pk_fma_f16 v17, v120, s51, v131 op_sel_hi:[1,0,0] neg_lo:[0,0,1] neg_hi:[0,0,1]
	v_pk_add_f16 v16, v42, v43
	v_pack_b32_f16 v38, v21, v20
	v_exp_f16_e32 v18, v17
	v_exp_f16_sdwa v17, v17 dst_sel:DWORD dst_unused:UNUSED_PAD src0_sel:WORD_1
	v_pk_fma_f16 v20, v121, s51, v131 op_sel_hi:[1,0,0] neg_lo:[0,0,1] neg_hi:[0,0,1]
	v_pk_add_f16 v16, v44, v16
	v_exp_f16_e32 v21, v20
	v_exp_f16_sdwa v20, v20 dst_sel:DWORD dst_unused:UNUSED_PAD src0_sel:WORD_1
	v_pack_b32_f16 v39, v18, v17
	v_pk_fma_f16 v17, v122, s51, v131 op_sel_hi:[1,0,0] neg_lo:[0,0,1] neg_hi:[0,0,1]
; #define LAS __attribute__((address_space(3)))
; __device__ __forceinline__ float shx(float v, int mask) { return __builtin_bit_cast(float, __builtin_amdgcn_ds_bpermute((lane_now() ^ mask) << 2, __builtin_bit_cast(int, v))); }
; __device__ __forceinline__ void attn_unit_lds(const f16* __restrict__ Q, f16* __restrict__ ATT, const LAS unsigned char* lds, const LAS float* bias, int b, int r, int h, int qb, int lane) {
;     ...
; #pragma unroll
;     for (int kr = 0; kr < 8; ++kr)
; #pragma unroll
;         for (int ct = 0; ct < 2; ++ct)
; #pragma unroll
;             for (int q = 0; q < 2; ++q) { const f16x2 a = sp[kr][ct][q] * (f16)1.44269504f - ml; f16x2 pe; pe[0] = __builtin_exp2f16(a[0]); pe[1] = __builtin_exp2f16(a[1]); sp[kr][ct][q] = pe; sumv += pe; }
;     float sum = (float)sumv[0] + (float)sumv[1];
;     sum += shx(sum, 16); sum += shx(sum, 32);
;     f32x4 o[4];
; #pragma unroll
;     for (int dt = 0; dt < 4; ++dt) o[dt] = (f32x4){0.f, 0.f, 0.f, 0.f};
;     const int ch = (c0k >> 3) + (g >> 1), hb = 8 * (g & 1);
; #pragma unroll
;     for (int kr = 0; kr < 8; ++kr) {
;         const int slot = ((rs + kr) % 9) * 16384 + 8192;
;         const f16x4 plo = __builtin_shufflevector(sp[kr][0][0], sp[kr][0][1], 0, 1, 2, 3), phi = __builtin_shufflevector(sp[kr][1][0], sp[kr][1][1], 0, 1, 2, 3);
;         const f16x8 pf = __builtin_shufflevector(plo, phi, 0, 1, 2, 3, 4, 5, 6, 7);
; #pragma unroll
;         for (int dt = 0; dt < 4; ++dt) {
;             const int d = 16 * dt + i, sw = (d >> 1) & 7; const LAS unsigned char* vp = lds + slot + d * 128 + hb;
;             const f16x4 v0 = *(const LAS f16x4*)(vp + ((ch ^ sw) * 16)), v1 = *(const LAS f16x4*)(vp + (((ch + 2) ^ sw) * 16));
	v_pk_add_f16 v16, v45, v16
	v_pack_b32_f16 v40, v21, v20
	v_exp_f16_e32 v18, v17
	v_exp_f16_sdwa v17, v17 dst_sel:DWORD dst_unused:UNUSED_PAD src0_sel:WORD_1
	v_pk_fma_f16 v20, v125, s51, v131 op_sel_hi:[1,0,0] neg_lo:[0,0,1] neg_hi:[0,0,1]
	v_pk_add_f16 v16, v38, v16
	v_exp_f16_e32 v21, v20
	v_exp_f16_sdwa v20, v20 dst_sel:DWORD dst_unused:UNUSED_PAD src0_sel:WORD_1
	v_pack_b32_f16 v41, v18, v17
	v_pk_fma_f16 v17, v128, s51, v131 op_sel_hi:[1,0,0] neg_lo:[0,0,1] neg_hi:[0,0,1]
	v_pk_add_f16 v16, v39, v16
	v_pack_b32_f16 v34, v21, v20
	v_exp_f16_e32 v18, v17
	v_exp_f16_sdwa v17, v17 dst_sel:DWORD dst_unused:UNUSED_PAD src0_sel:WORD_1
	v_pk_fma_f16 v20, v129, s51, v131 op_sel_hi:[1,0,0] neg_lo:[0,0,1] neg_hi:[0,0,1]
	v_pk_add_f16 v16, v40, v16
	v_exp_f16_e32 v21, v20
	v_exp_f16_sdwa v20, v20 dst_sel:DWORD dst_unused:UNUSED_PAD src0_sel:WORD_1
	v_pack_b32_f16 v35, v18, v17
	v_pk_fma_f16 v17, v116, s51, v131 op_sel_hi:[1,0,0] neg_lo:[0,0,1] neg_hi:[0,0,1]
	v_pk_add_f16 v16, v41, v16
	v_pack_b32_f16 v36, v21, v20
	v_exp_f16_e32 v18, v17
	v_exp_f16_sdwa v17, v17 dst_sel:DWORD dst_unused:UNUSED_PAD src0_sel:WORD_1
	v_pk_fma_f16 v20, v118, s51, v131 op_sel_hi:[1,0,0] neg_lo:[0,0,1] neg_hi:[0,0,1]
	v_pk_add_f16 v16, v34, v16
	v_exp_f16_e32 v21, v20
	v_exp_f16_sdwa v20, v20 dst_sel:DWORD dst_unused:UNUSED_PAD src0_sel:WORD_1
	v_pack_b32_f16 v37, v18, v17
	v_pk_fma_f16 v17, v130, s51, v131 op_sel_hi:[1,0,0] neg_lo:[0,0,1] neg_hi:[0,0,1]
	v_pk_add_f16 v16, v35, v16
	v_pack_b32_f16 v28, v21, v20
	v_exp_f16_e32 v18, v17
	v_exp_f16_sdwa v17, v17 dst_sel:DWORD dst_unused:UNUSED_PAD src0_sel:WORD_1
	v_pk_fma_f16 v20, v111, s51, v131 op_sel_hi:[1,0,0] neg_lo:[0,0,1] neg_hi:[0,0,1]
	v_pk_add_f16 v16, v36, v16
	v_exp_f16_e32 v21, v20
	v_exp_f16_sdwa v20, v20 dst_sel:DWORD dst_unused:UNUSED_PAD src0_sel:WORD_1
	v_pack_b32_f16 v29, v18, v17
	v_pk_fma_f16 v17, v115, s51, v131 op_sel_hi:[1,0,0] neg_lo:[0,0,1] neg_hi:[0,0,1]
	v_pk_add_f16 v16, v37, v16
	v_pack_b32_f16 v30, v21, v20
	v_exp_f16_e32 v18, v17
	v_exp_f16_sdwa v17, v17 dst_sel:DWORD dst_unused:UNUSED_PAD src0_sel:WORD_1
	v_pk_fma_f16 v20, v50, s51, v131 op_sel_hi:[1,0,0] neg_lo:[0,0,1] neg_hi:[0,0,1]
	v_pk_add_f16 v16, v28, v16
	v_exp_f16_e32 v21, v20
	v_exp_f16_sdwa v20, v20 dst_sel:DWORD dst_unused:UNUSED_PAD src0_sel:WORD_1
	v_pack_b32_f16 v31, v18, v17
	v_pk_fma_f16 v17, v52, s51, v131 op_sel_hi:[1,0,0] neg_lo:[0,0,1] neg_hi:[0,0,1]
	v_pk_add_f16 v16, v29, v16
	v_pack_b32_f16 v24, v21, v20
	v_exp_f16_e32 v18, v17
	v_exp_f16_sdwa v17, v17 dst_sel:DWORD dst_unused:UNUSED_PAD src0_sel:WORD_1
	v_pk_fma_f16 v20, v56, s51, v131 op_sel_hi:[1,0,0] neg_lo:[0,0,1] neg_hi:[0,0,1]
	v_pk_add_f16 v16, v30, v16
	v_exp_f16_e32 v21, v20
	v_exp_f16_sdwa v20, v20 dst_sel:DWORD dst_unused:UNUSED_PAD src0_sel:WORD_1
	v_pack_b32_f16 v25, v18, v17
	v_pk_fma_f16 v17, v54, s51, v131 op_sel_hi:[1,0,0] neg_lo:[0,0,1] neg_hi:[0,0,1]
	v_pk_add_f16 v16, v31, v16
	v_pack_b32_f16 v26, v21, v20
	v_exp_f16_e32 v18, v17
	v_exp_f16_sdwa v17, v17 dst_sel:DWORD dst_unused:UNUSED_PAD src0_sel:WORD_1
	v_pk_fma_f16 v20, v46, s51, v131 op_sel_hi:[1,0,0] neg_lo:[0,0,1] neg_hi:[0,0,1]
	v_pk_add_f16 v16, v24, v16
	v_exp_f16_e32 v21, v20
	v_exp_f16_sdwa v20, v20 dst_sel:DWORD dst_unused:UNUSED_PAD src0_sel:WORD_1
	v_pack_b32_f16 v27, v18, v17
	v_pk_fma_f16 v17, v47, s51, v131 op_sel_hi:[1,0,0] neg_lo:[0,0,1] neg_hi:[0,0,1]
	v_pk_add_f16 v16, v25, v16
	v_pack_b32_f16 v20, v21, v20
	v_exp_f16_e32 v18, v17
	v_exp_f16_sdwa v17, v17 dst_sel:DWORD dst_unused:UNUSED_PAD src0_sel:WORD_1
	v_pk_fma_f16 v21, v48, s51, v131 op_sel_hi:[1,0,0] neg_lo:[0,0,1] neg_hi:[0,0,1]
	v_pk_add_f16 v16, v26, v16
	v_exp_f16_e32 v22, v21
	v_exp_f16_sdwa v23, v21 dst_sel:DWORD dst_unused:UNUSED_PAD src0_sel:WORD_1
	v_pack_b32_f16 v21, v18, v17
	v_pk_fma_f16 v17, v49, s51, v131 op_sel_hi:[1,0,0] neg_lo:[0,0,1] neg_hi:[0,0,1]
	v_pk_add_f16 v16, v27, v16
	v_pack_b32_f16 v22, v22, v23
	v_exp_f16_e32 v18, v17
	v_exp_f16_sdwa v17, v17 dst_sel:DWORD dst_unused:UNUSED_PAD src0_sel:WORD_1
	v_pk_fma_f16 v23, v51, s51, v131 op_sel_hi:[1,0,0] neg_lo:[0,0,1] neg_hi:[0,0,1]
	v_pk_add_f16 v16, v20, v16
	v_exp_f16_e32 v46, v23
	v_exp_f16_sdwa v47, v23 dst_sel:DWORD dst_unused:UNUSED_PAD src0_sel:WORD_1
	v_pk_add_f16 v16, v21, v16
	v_pack_b32_f16 v23, v18, v17
	v_pk_add_f16 v16, v22, v16
	v_add3_u32 v50, s37, v98, v97
	v_pk_add_f16 v17, v23, v16
	v_pack_b32_f16 v16, v46, v47
	v_pk_add_f16 v18, v16, v17
	v_pk_fma_f16 v17, v53, s51, v131 op_sel_hi:[1,0,0] neg_lo:[0,0,1] neg_hi:[0,0,1]
	v_add_u32_e32 v106, v50, v99
	v_exp_f16_e32 v54, v17
	v_exp_f16_sdwa v17, v17 dst_sel:DWORD dst_unused:UNUSED_PAD src0_sel:WORD_1
	v_mbcnt_lo_u32_b32 v111, -1, 0
	v_mbcnt_hi_u32_b32 v111, -1, v111
	v_mbcnt_lo_u32_b32 v128, -1, 0
	v_mbcnt_hi_u32_b32 v128, -1, v128
	ds_read2st64_b64 v[46:49], v106 offset0:16 offset1:20
	v_pack_b32_f16 v17, v54, v17
	ds_read2st64_b64 v[106:109], v106 offset0:24 offset1:28
	v_pk_add_f16 v118, v17, v18
	v_pk_fma_f16 v18, v73, s51, v131 op_sel_hi:[1,0,0] neg_lo:[0,0,1] neg_hi:[0,0,1]
	v_add_u32_e32 v114, v50, v100
	v_exp_f16_e32 v73, v18
	v_exp_f16_sdwa v18, v18 dst_sel:DWORD dst_unused:UNUSED_PAD src0_sel:WORD_1
	ds_read2st64_b64 v[50:53], v114 offset0:16 offset1:20
	s_waitcnt lgkmcnt(2)
	v_mov_b32_e32 v54, v46
	s_waitcnt lgkmcnt(1)
	v_mov_b32_e32 v46, v106
	v_add3_u32 v106, s35, v98, v97
	v_pack_b32_f16 v18, v73, v18
	v_add_u32_e32 v129, v106, v99
	v_add_u32_e32 v130, v106, v100
	ds_read2st64_b64 v[114:117], v114 offset0:24 offset1:28
	v_pk_add_f16 v73, v18, v118
	ds_read2st64_b64 v[118:121], v129 offset0:16 offset1:20
	ds_read2st64_b64 v[122:125], v130 offset0:16 offset1:20
	v_mov_b32_e32 v55, v47
	s_waitcnt lgkmcnt(3)
; #define LAS __attribute__((address_space(3)))
; __device__ __forceinline__ void attn_unit_lds(const f16* __restrict__ Q, f16* __restrict__ ATT, const LAS unsigned char* lds, const LAS float* bias, int b, int r, int h, int qb, int lane) {
;     ...
;     const int ch = (c0k >> 3) + (g >> 1), hb = 8 * (g & 1);
; #pragma unroll
;     for (int kr = 0; kr < 8; ++kr) {
;         const int slot = ((rs + kr) % 9) * 16384 + 8192;
;         const f16x4 plo = __builtin_shufflevector(sp[kr][0][0], sp[kr][0][1], 0, 1, 2, 3), phi = __builtin_shufflevector(sp[kr][1][0], sp[kr][1][1], 0, 1, 2, 3);
;         const f16x8 pf = __builtin_shufflevector(plo, phi, 0, 1, 2, 3, 4, 5, 6, 7);
; #pragma unroll
;         for (int dt = 0; dt < 4; ++dt) {
;             const int d = 16 * dt + i, sw = (d >> 1) & 7; const LAS unsigned char* vp = lds + slot + d * 128 + hb;
;             const f16x4 v0 = *(const LAS f16x4*)(vp + ((ch ^ sw) * 16)), v1 = *(const LAS f16x4*)(vp + (((ch + 2) ^ sw) * 16));
;             f16x8 vf;
; #pragma unroll
;             for (int e = 0; e < 4; ++e) { vf[e] = v0[e]; vf[4 + e] = v1[e]; }
;             o[dt] = __builtin_amdgcn_mfma_f32_16x16x32_f16(vf, pf, o[dt], 0, 0, 0);
;         }
;     }
	v_mov_b32_e32 v56, v50
	v_mov_b32_e32 v57, v51
	v_mov_b32_e32 v50, v48
	v_mov_b32_e32 v51, v49
	v_mov_b32_e32 v47, v107
	s_waitcnt lgkmcnt(2)
	v_mov_b32_e32 v48, v114
	v_mov_b32_e32 v49, v115
	v_mov_b32_e32 v114, v108
	v_mov_b32_e32 v115, v109
	s_waitcnt lgkmcnt(1)
	v_mov_b32_e32 v106, v118
	v_mov_b32_e32 v107, v119
	s_waitcnt lgkmcnt(0)
	v_mov_b32_e32 v108, v122
	v_mov_b32_e32 v109, v123
	v_mfma_f32_16x16x32_f16 v[54:57], v[54:57], v[42:45], 0
	v_mov_b32_e32 v122, v120
	v_mov_b32_e32 v123, v121
	v_pk_fma_f16 v110, v110, s51, v131 op_sel_hi:[1,0,0] neg_lo:[0,0,1] neg_hi:[0,0,1]
	v_mfma_f32_16x16x32_f16 v[50:53], v[50:53], v[42:45], 0
	v_pk_fma_f16 v19, v19, s51, v131 op_sel_hi:[1,0,0] neg_lo:[0,0,1] neg_hi:[0,0,1]
	s_nop 0
	v_exp_f16_e32 v132, v19
	v_mfma_f32_16x16x32_f16 v[46:49], v[46:49], v[42:45], 0
	v_exp_f16_sdwa v19, v19 dst_sel:DWORD dst_unused:UNUSED_PAD src0_sel:WORD_1
	s_nop 0
	v_pack_b32_f16 v19, v132, v19
	v_mfma_f32_16x16x32_f16 v[42:45], v[114:117], v[42:45], 0
	ds_read2st64_b64 v[114:117], v129 offset0:24 offset1:28
	v_pk_add_f16 v73, v19, v73
	s_waitcnt lgkmcnt(0)
	v_mov_b32_e32 v118, v114
	v_mfma_f32_16x16x32_f16 v[54:57], v[106:109], v[38:41], v[54:57]
	ds_read2st64_b64 v[106:109], v130 offset0:24 offset1:28
	v_mov_b32_e32 v119, v115
	s_waitcnt lgkmcnt(0)
	v_mov_b32_e32 v120, v106
	v_mov_b32_e32 v121, v107
	v_add3_u32 v106, s34, v98, v97
	v_add_u32_e32 v129, v106, v99
	v_add_u32_e32 v130, v106, v100
	v_mfma_f32_16x16x32_f16 v[50:53], v[122:125], v[38:41], v[50:53]
	ds_read2st64_b64 v[122:125], v130 offset0:16 offset1:20
	v_mov_b32_e32 v106, v116
	v_mov_b32_e32 v107, v117
	v_mfma_f32_16x16x32_f16 v[46:49], v[118:121], v[38:41], v[46:49]
	ds_read2st64_b64 v[118:121], v129 offset0:16 offset1:20
	s_waitcnt lgkmcnt(1)
	v_mov_b32_e32 v116, v122
	v_mov_b32_e32 v117, v123
	v_mfma_f32_16x16x32_f16 v[40:43], v[106:109], v[38:41], v[42:45]
	ds_read2st64_b64 v[106:109], v129 offset0:24 offset1:28
	s_waitcnt lgkmcnt(1)
	v_mov_b32_e32 v114, v118
	v_mov_b32_e32 v115, v119
	v_mov_b32_e32 v122, v120
	v_mov_b32_e32 v123, v121
	v_mfma_f32_16x16x32_f16 v[54:57], v[114:117], v[34:37], v[54:57]
	ds_read2st64_b64 v[114:117], v130 offset0:24 offset1:28
	s_waitcnt lgkmcnt(1)
	v_mov_b32_e32 v118, v106
	v_mov_b32_e32 v119, v107
	v_mfma_f32_16x16x32_f16 v[50:53], v[122:125], v[34:37], v[50:53]
	v_exp_f16_e32 v38, v110
	s_waitcnt lgkmcnt(0)
	v_mov_b32_e32 v120, v114
	v_mov_b32_e32 v121, v115
	v_mov_b32_e32 v114, v108
	v_mov_b32_e32 v115, v109
	v_mfma_f32_16x16x32_f16 v[44:47], v[118:121], v[34:37], v[46:49]
	v_exp_f16_sdwa v39, v110 dst_sel:DWORD dst_unused:UNUSED_PAD src0_sel:WORD_1
	s_nop 1
	v_add3_u32 v48, s31, v98, v97
	v_add_u32_e32 v49, v48, v99
	v_add_u32_e32 v48, v48, v100
	ds_read2st64_b64 v[118:121], v49 offset0:16 offset1:20
	ds_read2st64_b64 v[122:125], v48 offset0:16 offset1:20
	v_mfma_f32_16x16x32_f16 v[34:37], v[114:117], v[34:37], v[40:43]
	v_pack_b32_f16 v38, v38, v39
	v_pk_fma_f16 v39, v112, s51, v131 op_sel_hi:[1,0,0] neg_lo:[0,0,1] neg_hi:[0,0,1]
	s_waitcnt lgkmcnt(1)
	v_mov_b32_e32 v106, v118
	v_mov_b32_e32 v107, v119
	s_waitcnt lgkmcnt(0)
	v_mov_b32_e32 v108, v122
	v_mov_b32_e32 v109, v123
	ds_read2st64_b64 v[40:43], v49 offset0:24 offset1:28
	v_mov_b32_e32 v122, v120
	v_mfma_f32_16x16x32_f16 v[54:57], v[106:109], v[28:31], v[54:57]
	ds_read2st64_b64 v[106:109], v48 offset0:24 offset1:28
	v_mov_b32_e32 v123, v121
	v_exp_f16_e32 v110, v39
	v_exp_f16_sdwa v39, v39 dst_sel:DWORD dst_unused:UNUSED_PAD src0_sel:WORD_1
	s_waitcnt lgkmcnt(1)
	v_mov_b32_e32 v114, v40
	v_mov_b32_e32 v115, v41
	s_waitcnt lgkmcnt(0)
	v_mov_b32_e32 v116, v106
	v_mov_b32_e32 v117, v107
	v_mov_b32_e32 v106, v42
	v_mov_b32_e32 v107, v43
	v_add3_u32 v40, s30, v98, v97
	v_mfma_f32_16x16x32_f16 v[48:51], v[122:125], v[28:31], v[50:53]
	v_pack_b32_f16 v39, v110, v39
	v_add_u32_e32 v110, v40, v100
	ds_read2st64_b64 v[118:121], v110 offset0:16 offset1:20
	v_add_u32_e32 v53, v40, v99
	v_mfma_f32_16x16x32_f16 v[44:47], v[114:117], v[28:31], v[44:47]
	ds_read2st64_b64 v[114:117], v53 offset0:16 offset1:20
	v_pk_fma_f16 v52, v126, s51, v131 op_sel_hi:[1,0,0] neg_lo:[0,0,1] neg_hi:[0,0,1]
	s_waitcnt lgkmcnt(1)
	v_mov_b32_e32 v42, v118
	v_mfma_f32_16x16x32_f16 v[28:31], v[106:109], v[28:31], v[34:37]
	ds_read2st64_b64 v[106:109], v110 offset0:24 offset1:28
	s_waitcnt lgkmcnt(1)
	v_mov_b32_e32 v40, v114
	v_mov_b32_e32 v41, v115
	ds_read2st64_b64 v[34:37], v53 offset0:24 offset1:28
	v_mov_b32_e32 v43, v119
	v_mov_b32_e32 v118, v116
	v_mov_b32_e32 v119, v117
	s_waitcnt lgkmcnt(1)
	v_mov_b32_e32 v116, v106
	s_waitcnt lgkmcnt(0)
	v_mov_b32_e32 v114, v34
	v_mov_b32_e32 v115, v35
	v_mov_b32_e32 v117, v107
	v_add3_u32 v34, s29, v98, v97
	v_exp_f16_e32 v112, v52
	v_exp_f16_sdwa v122, v52 dst_sel:DWORD dst_unused:UNUSED_PAD src0_sel:WORD_1
	v_mfma_f32_16x16x32_f16 v[52:55], v[40:43], v[24:27], v[54:57]
	v_mov_b32_e32 v106, v36
	v_mov_b32_e32 v107, v37
	v_pk_fma_f16 v41, v127, s51, v131 op_sel_hi:[1,0,0] neg_lo:[0,0,1] neg_hi:[0,0,1]
	v_mfma_f32_16x16x32_f16 v[42:45], v[114:117], v[24:27], v[44:47]
	v_exp_f16_e32 v57, v41
	v_exp_f16_sdwa v41, v41 dst_sel:DWORD dst_unused:UNUSED_PAD src0_sel:WORD_1
	v_pk_add_f16 v73, v38, v73
	v_add_u32_e32 v46, v34, v99
	v_add_u32_e32 v47, v34, v100
	v_mfma_f32_16x16x32_f16 v[48:51], v[118:121], v[24:27], v[48:51]
	ds_read2st64_b64 v[114:117], v46 offset0:16 offset1:20
	ds_read2st64_b64 v[118:121], v47 offset0:16 offset1:20
	v_pk_add_f16 v73, v39, v73
	v_mfma_f32_16x16x32_f16 v[24:27], v[106:109], v[24:27], v[28:31]
	v_pack_b32_f16 v40, v112, v122
	s_waitcnt lgkmcnt(1)
; #define LAS __attribute__((address_space(3)))
; __device__ __forceinline__ void attn_unit_lds(const f16* __restrict__ Q, f16* __restrict__ ATT, const LAS unsigned char* lds, const LAS float* bias, int b, int r, int h, int qb, int lane) {
;     ...
;     float sum = (float)sumv[0] + (float)sumv[1];
;     sum += shx(sum, 16); sum += shx(sum, 32);
;     f32x4 o[4];
; #pragma unroll
;     for (int dt = 0; dt < 4; ++dt) o[dt] = (f32x4){0.f, 0.f, 0.f, 0.f};
;     const int ch = (c0k >> 3) + (g >> 1), hb = 8 * (g & 1);
; #pragma unroll
;     for (int kr = 0; kr < 8; ++kr) {
;         const int slot = ((rs + kr) % 9) * 16384 + 8192;
;         const f16x4 plo = __builtin_shufflevector(sp[kr][0][0], sp[kr][0][1], 0, 1, 2, 3), phi = __builtin_shufflevector(sp[kr][1][0], sp[kr][1][1], 0, 1, 2, 3);
;         const f16x8 pf = __builtin_shufflevector(plo, phi, 0, 1, 2, 3, 4, 5, 6, 7);
; #pragma unroll
;         for (int dt = 0; dt < 4; ++dt) {
;             const int d = 16 * dt + i, sw = (d >> 1) & 7; const LAS unsigned char* vp = lds + slot + d * 128 + hb;
;             const f16x4 v0 = *(const LAS f16x4*)(vp + ((ch ^ sw) * 16)), v1 = *(const LAS f16x4*)(vp + (((ch + 2) ^ sw) * 16));
;             f16x8 vf;
; #pragma unroll
;             for (int e = 0; e < 4; ++e) { vf[e] = v0[e]; vf[4 + e] = v1[e]; }
;             o[dt] = __builtin_amdgcn_mfma_f32_16x16x32_f16(vf, pf, o[dt], 0, 0, 0);
;         }
;     }
;     const float inv = 1.0f / sum;
;     f16* op = ATT + (size_t)(b * SEQ + r * GW + qc) * DA + h * HD + 4 * g;
; #pragma unroll
;     for (int dt = 0; dt < 4; ++dt) { u32x2 w; w.x = rd<D_AMIX>(pk_f16(o[dt][0] * inv, o[dt][1] * inv)); w.y = rd<D_AMIX>(pk_f16(o[dt][2] * inv, o[dt][3] * inv)); *(u32x2*)(op + 16 * dt) = w; }
; __device__ __forceinline__ void attn_block(const f16* __restrict__ Q, const f16* __restrict__ Kb, const f16* __restrict__ VT, f16* __restrict__ ATT, const float* __restrict__ rpb_h,
;                                            LAS unsigned char* lds, int b, int h, int rc, int tid, int wave, int lane) {
;     ...
;         __syncthreads();
;         if (nlo < nhi) { const int slot = (nlo % 9) * 16384; *(LAS u32x4*)(lds + slot + sdst) = pk0; *(LAS u32x4*)(lds + slot + 8192 + sdst) = pv0; }
;         if (nlo + 1 < nhi) { const int slot = ((nlo + 1) % 9) * 16384; *(LAS u32x4*)(lds + slot + sdst) = pk1; *(LAS u32x4*)(lds + slot + 8192 + sdst) = pv1; }
	v_mov_b32_e32 v34, v114
	v_mov_b32_e32 v35, v115
	s_waitcnt lgkmcnt(0)
	v_mov_b32_e32 v36, v118
	v_mov_b32_e32 v37, v119
	ds_read2st64_b64 v[28:31], v46 offset0:24 offset1:28
	v_mov_b32_e32 v118, v116
	v_mfma_f32_16x16x32_f16 v[34:37], v[34:37], v[20:23], v[52:55]
	v_mov_b32_e32 v119, v117
	s_nop 1
	ds_read2st64_b64 v[52:55], v47 offset0:24 offset1:28
	s_waitcnt lgkmcnt(1)
	v_mov_b32_e32 v106, v28
	v_mov_b32_e32 v107, v29
	v_pk_add_f16 v56, v40, v73
	v_pack_b32_f16 v41, v57, v41
	s_waitcnt lgkmcnt(0)
	v_mov_b32_e32 v108, v52
	v_mov_b32_e32 v109, v53
	v_mfma_f32_16x16x32_f16 v[46:49], v[118:121], v[20:23], v[48:51]
	v_mov_b32_e32 v52, v30
	v_mov_b32_e32 v53, v31
	s_nop 0
	v_pk_add_f16 v50, v41, v56
	v_add3_u32 v56, s28, v98, v97
	v_add_u32_e32 v57, v56, v99
	v_add_u32_e32 v56, v56, v100
	v_mfma_f32_16x16x32_f16 v[42:45], v[106:109], v[20:23], v[42:45]
	ds_read2st64_b64 v[28:31], v57 offset0:16 offset1:20
	ds_read2st64_b64 v[106:109], v56 offset0:16 offset1:20
	v_cvt_f32_f16_e32 v51, v50
	v_mfma_f32_16x16x32_f16 v[20:23], v[52:55], v[20:23], v[24:27]
	v_cvt_f32_f16_sdwa v50, v50 dst_sel:DWORD dst_unused:UNUSED_PAD src0_sel:WORD_1
	v_add_f32_e32 v73, v50, v51
	s_waitcnt lgkmcnt(1)
	v_mov_b32_e32 v24, v28
	v_mov_b32_e32 v25, v29
	s_waitcnt lgkmcnt(0)
	v_mov_b32_e32 v26, v106
	v_mov_b32_e32 v27, v107
	v_mov_b32_e32 v106, v30
	v_mov_b32_e32 v107, v31
	v_mfma_f32_16x16x32_f16 v[24:27], v[24:27], v[16:19], v[34:37]
	ds_read2st64_b64 v[50:53], v57 offset0:24 offset1:28
	s_nop 1
	ds_read2st64_b64 v[34:37], v56 offset0:24 offset1:28
	s_waitcnt lgkmcnt(1)
	v_mov_b32_e32 v28, v50
	s_waitcnt lgkmcnt(0)
	v_mov_b32_e32 v30, v34
	v_lshlrev_b32_e32 v34, 2, v111
	v_xor_b32_e32 v34, 64, v34
	v_mfma_f32_16x16x32_f16 v[46:49], v[106:109], v[16:19], v[46:49]
	ds_bpermute_b32 v106, v34, v73
	v_add3_u32 v34, s27, v98, v97
	v_mov_b32_e32 v29, v51
	v_mov_b32_e32 v31, v35
	v_add_u32_e32 v107, v34, v99
	v_add_u32_e32 v108, v34, v100
	v_mov_b32_e32 v34, v52
	v_mov_b32_e32 v35, v53
	v_mfma_f32_16x16x32_f16 v[28:31], v[28:31], v[16:19], v[42:45]
	s_waitcnt lgkmcnt(0)
	v_add_f32_e32 v73, v73, v106
	v_lshlrev_b32_e32 v106, 2, v128
	ds_read2st64_b64 v[54:57], v108 offset0:16 offset1:20
	ds_read2st64_b64 v[42:45], v107 offset0:16 offset1:20
	v_mfma_f32_16x16x32_f16 v[16:19], v[34:37], v[16:19], v[20:23]
	ds_read2st64_b64 v[34:37], v108 offset0:24 offset1:28
	s_waitcnt lgkmcnt(2)
	v_mov_b32_e32 v52, v54
	ds_read2st64_b64 v[20:23], v107 offset0:24 offset1:28
	s_waitcnt lgkmcnt(2)
	v_mov_b32_e32 v50, v42
	v_mov_b32_e32 v51, v43
	v_mov_b32_e32 v54, v44
	s_waitcnt lgkmcnt(1)
	v_mov_b32_e32 v44, v34
	s_waitcnt lgkmcnt(0)
	v_mov_b32_e32 v42, v20
	v_xor_b32_e32 v20, 0x80, v106
	ds_bpermute_b32 v20, v20, v73
	v_mov_b32_e32 v43, v21
	v_mov_b32_e32 v34, v22
	v_mov_b32_e32 v53, v55
	v_mov_b32_e32 v55, v45
	s_waitcnt lgkmcnt(0)
	v_add_f32_e32 v20, v73, v20
	v_div_scale_f32 v21, s[28:29], v20, v20, 1.0
	v_rcp_f32_e32 v22, v21
	v_mov_b32_e32 v45, v35
	v_mov_b32_e32 v35, v23
	v_mfma_f32_16x16x32_f16 v[24:27], v[50:53], v[38:41], v[24:27]
	v_fma_f32 v23, -v21, v22, 1.0
	v_fmac_f32_e32 v22, v23, v22
	v_div_scale_f32 v23, vcc, 1.0, v20, 1.0
	v_mfma_f32_16x16x32_f16 v[16:19], v[34:37], v[38:41], v[16:19]
	v_mul_f32_e32 v34, v23, v22
	v_fma_f32 v35, -v21, v34, v23
	v_fmac_f32_e32 v34, v35, v22
	v_fma_f32 v21, -v21, v34, v23
	v_div_fmas_f32 v21, v21, v22, v34
	v_div_fixup_f32 v34, v21, v20, 1.0
	v_mul_f32_e32 v22, v34, v24
	v_mul_f32_e32 v23, v34, v25
	v_mfma_f32_16x16x32_f16 v[46:49], v[54:57], v[38:41], v[46:49]
	v_cvt_pk_f16_f32 v22, v22, v23
	v_mul_f32_e32 v23, v34, v26
	v_mul_f32_e32 v24, v34, v27
	v_cvt_pk_f16_f32 v23, v23, v24
	v_add_u32_e32 v22, 0x100010, v22
	v_add_u32_e32 v23, 0x100010, v23
	v_lshl_add_u64 v[20:21], v[76:77], 0, v[78:79]
	v_and_b32_e32 v22, 0xffe0ffe0, v22
	v_and_b32_e32 v23, 0xffe0ffe0, v23
	global_store_dwordx2 v[20:21], v[22:23], off
	v_mul_f32_e32 v22, v34, v46
	v_mul_f32_e32 v23, v34, v47
	v_mfma_f32_16x16x32_f16 v[28:31], v[42:45], v[38:41], v[28:31]
	v_cvt_pk_f16_f32 v22, v22, v23
	v_mul_f32_e32 v23, v34, v48
	v_mul_f32_e32 v24, v34, v49
	v_cvt_pk_f16_f32 v23, v23, v24
	v_add_u32_e32 v22, 0x100010, v22
	v_add_u32_e32 v23, 0x100010, v23
	v_and_b32_e32 v22, 0xffe0ffe0, v22
	v_and_b32_e32 v23, 0xffe0ffe0, v23
	global_store_dwordx2 v[20:21], v[22:23], off offset:32
	v_mul_f32_e32 v22, v34, v28
	v_mul_f32_e32 v23, v34, v29
	v_mul_f32_e32 v16, v34, v16
	v_mul_f32_e32 v17, v34, v17
	v_cvt_pk_f16_f32 v22, v22, v23
	v_mul_f32_e32 v23, v34, v30
	v_mul_f32_e32 v24, v34, v31
	v_cvt_pk_f16_f32 v16, v16, v17
	v_mul_f32_e32 v17, v34, v18
	v_mul_f32_e32 v18, v34, v19
	v_cvt_pk_f16_f32 v23, v23, v24
	v_cvt_pk_f16_f32 v17, v17, v18
	v_add_u32_e32 v22, 0x100010, v22
	v_add_u32_e32 v23, 0x100010, v23
	v_add_u32_e32 v16, 0x100010, v16
	v_add_u32_e32 v17, 0x100010, v17
	v_and_b32_e32 v22, 0xffe0ffe0, v22
	v_and_b32_e32 v23, 0xffe0ffe0, v23
	v_and_b32_e32 v16, 0xffe0ffe0, v16
	v_and_b32_e32 v17, 0xffe0ffe0, v17
	s_andn2_b64 vcc, exec, s[2:3]
	global_store_dwordx2 v[20:21], v[22:23], off offset:64
	global_store_dwordx2 v[20:21], v[16:17], off offset:96
	s_barrier
	s_cbranch_vccnz .LBB0_654
	s_mul_i32 s2, s25, 57
	s_lshr_b32 s2, s2, 9
	s_mul_i32 s2, s2, 9
	s_sub_i32 s2, s25, s2
	s_and_b32 s2, s2, 0xff
	v_lshl_add_u32 v16, s2, 14, v103
	ds_write_b128 v16, v[4:7]
	ds_write_b128 v16, v[8:11] offset:8192
